# banded attention loop: softmax priority lowered from 3 to 1 so the dense loops' MFMA phases (prio 2) on the partner block win arbitration
# baseline (speedup 1.0000x reference)
; #define MFMA(a, b, c) __builtin_amdgcn_mfma_f32_32x32x16_bf16((a), (b), (c), 0, 0, 0)
; template <int DQK, bool BAND, int QT> ...
;     ...
;     if (need) {
;       f32x16 s[2][QT];
; #pragma unroll
;       for (int a = 0; a < 2; ++a)
; #pragma unroll
;         for (int b = 0; b < QT; ++b)
; #pragma unroll
;           for (int r = 0; r < 16; ++r) s[a][b][r] = 0.f;
; #pragma unroll
;       for (int ks = 0; ks < NKS; ++ks) {
;         const bf16x8 k0 = *(const bf16x8*)(st + k_rd + ks * 32);
;         const bf16x8 k1 = *(const bf16x8*)(st + k_rd + 32 * KROW + ks * 32);
; #pragma unroll
;         for (int qt = 0; qt < QT; ++qt) {
;           s[0][qt] = MFMA(k0, qf[qt][ks], s[0][qt]);
;           s[1][qt] = MFMA(k1, qf[qt][ks], s[1][qt]);
;         }
;       }
;       __builtin_amdgcn_s_setprio(3);
;       bf16x8 pf[QT][4];
;       const float cc = BAND ? 1.0f : scale_log2;
;       const float th = BAND ? 8.0f : 8.0f / scale_log2;
; #pragma unroll
;       for (int qt = 0; qt < QT; ++qt) {
;         if (BAND) {
; #pragma unroll
;           for (int a = 0; a < 2; ++a)
; #pragma unroll
;             for (int r = 0; r < 16; ++r) {
;               const int kidx = kt + 32 * a + (r & 7) + 8 * h + 16 * (r >> 3);
;               const int rel = kidx - (qw0 + qt * 32 + ql);
;               const bool ok = (rel >= -64) && (rel <= 64);
;               const int bi = ok ? rel + 64 : 0;
;               s[a][qt][r] = ok ? fmaf(s[a][qt][r], scale_log2, bias_l[bi]) : -1e30f;
.LBB0_684:
	s_andn2_saveexec_b64 s[0:1], s[0:1]
	s_cbranch_execz .LBB0_678
	s_bitcmp1_b32 s35, 0
	s_cselect_b32 s6, 0x4800, 0
	s_add_i32 s72, s6, 0
	v_add3_u32 v216, s72, v185, v0
	ds_read_b128 v[80:83], v216 offset:4608
	ds_read_b128 v[84:87], v216
	ds_read_b128 v[208:211], v216 offset:32
	ds_read_b128 v[212:215], v216 offset:4640
	s_waitcnt lgkmcnt(3)
	v_mfma_f32_32x32x16_bf16 v[112:127], v[80:83], v[2:5], 0
	s_waitcnt lgkmcnt(2)
	v_mfma_f32_32x32x16_bf16 v[128:143], v[84:87], v[2:5], 0
	v_mfma_f32_32x32x16_bf16 v[96:111], v[84:87], v[148:151], 0
	v_mfma_f32_32x32x16_bf16 v[80:95], v[80:83], v[148:151], 0
	s_waitcnt lgkmcnt(1)
	v_mfma_f32_32x32x16_bf16 v[128:143], v[208:211], v[6:9], v[128:143]
	s_waitcnt lgkmcnt(0)
	v_mfma_f32_32x32x16_bf16 v[112:127], v[212:215], v[6:9], v[112:127]
	v_mfma_f32_32x32x16_bf16 v[96:111], v[208:211], v[152:155], v[96:111]
	v_mfma_f32_32x32x16_bf16 v[80:95], v[212:215], v[152:155], v[80:95]
	ds_read_b128 v[208:211], v216 offset:64
	ds_read_b128 v[212:215], v216 offset:4672
	s_waitcnt lgkmcnt(1)
	v_mfma_f32_32x32x16_bf16 v[128:143], v[208:211], v[10:13], v[128:143]
	s_waitcnt lgkmcnt(0)
	v_mfma_f32_32x32x16_bf16 v[112:127], v[212:215], v[10:13], v[112:127]
	v_mfma_f32_32x32x16_bf16 v[96:111], v[208:211], v[156:159], v[96:111]
	v_mfma_f32_32x32x16_bf16 v[80:95], v[212:215], v[156:159], v[80:95]
	ds_read_b128 v[208:211], v216 offset:96
	ds_read_b128 v[212:215], v216 offset:4704
	s_waitcnt lgkmcnt(1)
	v_mfma_f32_32x32x16_bf16 v[128:143], v[208:211], v[144:147], v[128:143]
	s_waitcnt lgkmcnt(0)
	v_mfma_f32_32x32x16_bf16 v[112:127], v[212:215], v[144:147], v[112:127]
	v_mfma_f32_32x32x16_bf16 v[96:111], v[208:211], v[160:163], v[96:111]
	v_mfma_f32_32x32x16_bf16 v[80:95], v[212:215], v[160:163], v[80:95]
	s_setprio 1
	v_add_u32_e32 v215, s4, v207
	v_cmp_gt_u32_e64 s[40:41], s18, v215
	v_mov_b32_e32 v208, 0xf149f2ca
	v_mov_b32_e32 v209, 0xf149f2ca
	s_and_saveexec_b64 s[42:43], s[40:41]
	s_cbranch_execz .LBB0_687
	ds_read_b32 v209, v206 offset:128
	s_waitcnt lgkmcnt(0)
	v_fmac_f32_e32 v209, 0x3e38aa3b, v128
